# layer-1 w_in post pass: 3-unit workgroups take over one post unit of a same-XCC 4-unit workgroup (claim bits in zeroed workspace words)
# speedup vs baseline: 1.0539x; 1.0193x over previous
.LBB0_992:
	s_mov_b32 s0, 0
	s_movk_i32 s6, 0x210
	v_mbcnt_lo_u32_b32 v0, -1, s0
	v_mbcnt_hi_u32_b32 v1, -1, v0
	v_readlane_b32 s0, v254, 7
	v_and_b32_e32 v6, 31, v1
	v_and_b32_e32 v12, 7, v1
	v_add_u32_e32 v3, s0, v1
	v_bfe_u32 v15, v3, 6, 1
	v_lshlrev_b32_e32 v4, 5, v1
	v_bfe_u32 v14, v3, 7, 1
	v_lshl_or_b32 v6, v15, 5, v6
	v_lshrrev_b32_e32 v1, 2, v1
	v_mad_u32_u24 v6, v6, s6, 0
	v_lshlrev_b32_e32 v7, 5, v14
	v_and_b32_e32 v1, 8, v1
	v_ashrrev_i32_e32 v87, 3, v3
	v_add_u32_e32 v16, 0x200, v3
	v_and_b32_e32 v5, 0xc0, v4
	v_and_b32_e32 v4, 32, v4
	v_add3_u32 v1, v6, v7, v1
	v_ashrrev_i32_e32 v88, 3, v16
	v_add_u32_e32 v17, 0x400, v3
	v_and_b32_e32 v6, 31, v87
	v_ashrrev_i32_e32 v89, 3, v17
	v_add_u32_e32 v18, 0x600, v3
	v_or3_b32 v19, v6, v5, v4
	v_and_b32_e32 v6, 31, v88
	v_ashrrev_i32_e32 v90, 3, v18
	v_or3_b32 v20, v5, v6, v4
	v_and_b32_e32 v6, 31, v89
	v_or3_b32 v21, v5, v6, v4
	v_and_b32_e32 v6, 31, v90
	v_or3_b32 v22, v5, v6, v4
	v_ashrrev_i32_e32 v4, 5, v3
	s_load_dwordx2 s[4:5], s[82:83], 0xa8
	v_and_b32_e32 v4, -8, v4
	v_ashrrev_i32_e32 v6, 5, v16
	v_ashrrev_i32_e32 v8, 5, v17
	v_ashrrev_i32_e32 v10, 5, v18
	v_ashrrev_i32_e32 v5, 31, v4
	v_and_b32_e32 v6, -8, v6
	v_and_b32_e32 v8, -8, v8
	v_and_b32_e32 v10, -8, v10
	v_ashrrev_i32_e32 v7, 31, v6
	v_mul_lo_u32 v23, v4, s6
	v_mul_lo_u32 v48, v6, s6
	v_mul_lo_u32 v49, v8, s6
	v_mul_lo_u32 v50, v10, s6
	s_waitcnt lgkmcnt(0)
	v_lshl_add_u64 v[4:5], v[4:5], 1, s[8:9]
	s_mov_b64 s[6:7], 0x9600000
	s_add_u32 s0, s8, 0x100000
	v_ashrrev_i32_e32 v9, 31, v8
	v_lshl_add_u64 v[36:37], v[4:5], 0, s[6:7]
	v_lshl_add_u64 v[4:5], v[6:7], 1, s[8:9]
	s_addc_u32 s1, s9, 0
	v_lshlrev_b32_e32 v2, 3, v3
	v_and_b32_e32 v86, 0xff, v3
	v_ashrrev_i32_e32 v11, 31, v10
	v_ashrrev_i32_e32 v91, 8, v3
	v_lshl_add_u64 v[38:39], v[4:5], 0, s[6:7]
	v_lshl_add_u64 v[4:5], v[8:9], 1, s[8:9]
	v_and_b32_e32 v3, 7, v3
	s_add_u32 s2, s4, 0x2000000
	v_mov_b32_e32 v25, 0
	v_lshl_add_u64 v[40:41], v[4:5], 0, s[6:7]
	v_lshl_add_u64 v[4:5], v[10:11], 1, s[8:9]
	v_lshlrev_b32_e32 v24, 4, v3
	s_addc_u32 s20, s5, 0
	v_lshlrev_b32_e32 v15, 10, v15
	v_ashrrev_i32_e32 v92, 8, v16
	v_ashrrev_i32_e32 v93, 8, v17
	v_ashrrev_i32_e32 v94, 8, v18
	v_lshl_add_u64 v[42:43], v[4:5], 0, s[6:7]
	v_lshl_add_u64 v[4:5], s[8:9], 0, v[24:25]
	v_lshlrev_b32_e32 v24, 4, v12
	s_add_u32 s21, s8, 0x300000
	v_and_b32_e32 v0, 56, v2
	v_lshl_add_u32 v13, v86, 1, 0
	v_and_b32_e32 v2, 0x1f8, v2
	v_lshlrev_b32_e32 v51, 6, v91
	v_lshl_or_b32 v26, v14, 11, v15
	v_lshlrev_b32_e32 v14, 6, v92
	v_lshlrev_b32_e32 v15, 6, v93
	v_lshlrev_b32_e32 v16, 6, v94
	v_lshl_add_u64 v[44:45], v[4:5], 0, s[6:7]
	v_lshl_add_u64 v[4:5], s[8:9], 0, v[24:25]
	s_addc_u32 s22, s9, 0
	v_mov_b32_e32 v27, v25
	v_lshlrev_b32_e32 v28, 4, v19
	v_mov_b32_e32 v29, v25
	v_lshlrev_b32_e32 v30, 4, v20
	v_mov_b32_e32 v31, v25
	v_lshlrev_b32_e32 v32, 4, v21
	v_mov_b32_e32 v33, v25
	v_lshlrev_b32_e32 v34, 4, v22
	v_mov_b32_e32 v35, v25
	v_lshl_add_u64 v[46:47], v[4:5], 0, s[6:7]
	s_movk_i32 s23, 0x67
	v_lshlrev_b32_e32 v24, 1, v2
	s_movk_i32 s24, 0x1800
	v_lshlrev_b32_e32 v95, 2, v0
	v_mov_b32_e32 v96, 0x358637bd
	v_add_u32_e32 v97, v13, v23
	v_add_u32_e32 v98, v13, v48
	v_add_u32_e32 v99, v13, v49
	v_add_u32_e32 v100, v13, v50
	v_add_u32_e32 v101, v1, v51
	v_add_u32_e32 v102, v1, v14
	v_add_u32_e32 v103, v1, v15
	v_add_u32_e32 v104, v1, v16
	v_mov_b64_e32 v[48:49], 0x32f
	v_mov_b64_e32 v[50:51], 0x330
	v_mov_b32_e32 v105, 0x3e38aa3b
	s_cmp_lg_u32 s74, 0x100
	s_cbranch_scc1 .Lps_generic
	s_cmp_lg_u32 s75, 0
	s_cbranch_scc1 .Lps_generic
	s_mov_b32 s94, s93
	s_mov_b32 s95, -1
	s_getreg_b32 s96, hwreg(HW_REG_XCC_ID, 0, 4)
	s_and_b32 s96, s96, 15
	s_load_dwordx2 s[40:41], s[82:83], 0xb0
	s_mov_b64 s[38:39], 0
	s_and_b64 vcc, exec, s[86:87]
	s_cbranch_vccz .Lps_nolead
	v_mbcnt_lo_u32_b32 v122, -1, 0
	v_mbcnt_hi_u32_b32 v122, -1, v122
	v_cmp_eq_u32_e32 vcc, 0, v122
	s_and_b64 s[38:39], vcc, exec
.Lps_nolead:
	s_waitcnt lgkmcnt(0)
	s_add_u32 s40, s40, 0x3600
	s_addc_u32 s41, s41, 0
	s_cmp_lt_u32 s94, 48
	s_cselect_b32 s97, 1, 0
	s_waitcnt vmcnt(0)
	s_barrier
	s_cmp_eq_u32 s97, 0
	s_cbranch_scc1 .Lps_next
	s_and_saveexec_b64 s[42:43], s[38:39]
	s_cbranch_execz .Lps_pub_done
	s_add_u32 s44, s96, 1
	s_lshl_b32 s45, s94, 2
	v_mov_b32_e32 v122, s45
	v_mov_b32_e32 v123, s44
	global_atomic_or v122, v123, s[40:41]
.Lps_pub_done:
	s_or_b64 exec, exec, s[42:43]
.Lps_next:
	s_add_i32 s95, s95, 1
	s_cmp_gt_u32 s95, 3
	s_cbranch_scc1 .Lps_exit
	s_cmp_eq_u32 s97, 0
	s_cbranch_scc1 .Lps_light
	s_mov_b32 s46, s94
	s_mov_b32 s48, 0
	s_mov_b32 s47, 3
	s_cmp_eq_u32 s95, 0
	s_cbranch_scc1 .Lps_run
	s_add_i32 s47, s95, -1
	s_branch .Lps_claim
.Lps_light:
	s_mov_b32 s46, s94
	s_mov_b32 s47, s95
	s_cmp_lt_u32 s95, 3
	s_cbranch_scc1 .Lps_run
	s_add_i32 s44, s94, -48
	s_lshr_b32 s44, s44, 3
	s_cmp_gt_u32 s44, 17
	s_cbranch_scc1 .Lps_exit
	s_mul_i32 s45, s44, 43
	s_lshr_b32 s45, s45, 7
	s_mul_i32 s47, s45, 3
	s_sub_u32 s47, s44, s47
	s_and_b32 s46, s94, 7
	s_lshl3_add_u32 s46, s45, s46
	s_mov_b32 s48, 1
.Lps_claim:
	s_mov_b32 s49, 0
	s_and_saveexec_b64 s[42:43], s[38:39]
	s_cbranch_execz .Lps_cl_done
	s_lshl_b32 s44, s46, 2
	v_mov_b32_e32 v122, s44
	s_cmp_eq_u32 s48, 0
	s_cbranch_scc1 .Lps_cl_try
	s_mov_b32 s45, 0
.Lps_cl_poll:
	global_load_dword v124, v122, s[40:41] sc1
	s_waitcnt vmcnt(0)
	v_readfirstlane_b32 s50, v124
	s_and_b32 s51, s50, 31
	s_cmp_lg_u32 s51, 0
	s_cbranch_scc1 .Lps_cl_ready
	s_add_u32 s45, s45, 1
	s_cmp_lt_u32 s45, 100
	s_cbranch_scc0 .Lps_cl_write
	s_sleep 8
	s_branch .Lps_cl_poll
.Lps_cl_ready:
	s_add_i32 s51, s51, -1
	s_cmp_lg_u32 s51, s96
	s_cbranch_scc1 .Lps_cl_write
.Lps_cl_try:
	s_add_u32 s51, s47, 8
	s_lshl_b32 s51, 1, s51
	v_mov_b32_e32 v123, s51
	global_atomic_or v124, v122, v123, s[40:41] sc0
	s_waitcnt vmcnt(0)
	v_readfirstlane_b32 s50, v124
	s_and_b32 s50, s50, s51
	s_cmp_eq_u32 s50, 0
	s_cselect_b32 s49, 1, 0
	buffer_inv sc1
	s_waitcnt vmcnt(0)
.Lps_cl_write:
	v_mov_b32_e32 v123, s49
	v_mov_b32_e32 v125, 0x25010
	ds_write_b32 v125, v123
	s_waitcnt lgkmcnt(0)
.Lps_cl_done:
	s_or_b64 exec, exec, s[42:43]
	s_barrier
	v_mov_b32_e32 v125, 0x25010
	ds_read_b32 v123, v125
	s_waitcnt lgkmcnt(0)
	v_readfirstlane_b32 s49, v123
	s_barrier
	s_cmp_eq_u32 s49, 0
	s_cbranch_scc1 .Lps_next
.Lps_run:
	s_mov_b32 s93, s46
	s_mov_b32 s36, s47
	s_branch .LBB0_995
.Lps_generic:
	s_movk_i32 s95, 0xff
	s_branch .LBB0_995
.LBB0_993:
	s_cmpk_eq_u32 s95, 0xff
	s_cbranch_scc0 .Lps_next
	s_add_i32 s36, s36, 1
	s_mov_b64 s[6:7], 0

.Lps_exit:
	s_cmpk_eq_u32 s95, 0xff
	s_cbranch_scc1 .LBB0_1026
	s_mov_b32 s93, s94
